# GEMM unit boundary: trailing half's re-stagger barrier moved behind its unit scheduling header
# speedup vs baseline: 1.0074x; 1.0074x over previous
.Lk_restag:
	v_readlane_b32 s51, v232, 6
	s_cmp_eq_u32 s51, 0
	s_cbranch_scc1 .Lk_peel
	s_barrier
	s_branch .Lk_peel
